# FoX and MLA loops: K/V prefetch addressing via SGPR base + loop-invariant lane offsets (removes 110-150 VALU per tile)
# speedup vs baseline: 1.0172x; 1.0172x over previous
; DI int otid() { int z; asm volatile("s_mov_b32 %0, 0" : "=s"(z)); return (int)threadIdx.x + z; }
;   DI float aux(int key) const { return (cuml[key] + cpre[key >> 7]) * LOG2E; }
;           DI float aux(int key) const { int n = key < 511 ? key : 510; return __int_as_float(pos[16 * n + 31]); }
;   DI int next(int t) const { for (int j = t + 1; j < 128; ++j) if (inu(j) && !farj(j)) return j; return -1; }
; template <int DK, bool PV, bool PF, class Ctx>
; DI void attn_run(const bf16x8 (&qf)[DK / 16], f32x16 (&o)[4], float& m, float& l, const bf16* K1, int ldk1,
;                  const bf16* K2, int ldk2, const bf16* Vt, int ldv, int first, Ctx& ctx, char* smem) {
;     ...
;   auto ldk = [&](int i, int key0) -> uint4 {
;     int c = otid() + 256 * i;
;     int row = c / CPR, cc = c % CPR;
;     const bf16* src;
;     if (DK == 128 || cc < 16) src = K1 + (size_t)(key0 + row) * ldk1 + cc * 8;
;     else src = K2 + (size_t)(key0 + row) * ldk2 + (cc - 16) * 8;
;     return *(const uint4*)src;
;   };
;   auto stk = [&](int i, const uint4& v) {
;     int c = tid + 256 * i;
;     int row = c / CPR, cc = c % CPR;
;     *(uint4*)(Ks + row * (DK + 8) + cc * 8) = v;
;   };
;   auto gload = [&](int key0) {
;     rk0 = ldk(0, key0); rk1 = ldk(1, key0); rk2 = ldk(2, key0); rk3 = ldk(3, key0);
;     if (NKC > 4) { rk4 = ldk(4, key0); rk5 = ldk(5, key0); }
;     const int tl = otid();
; #pragma unroll
;     for (int i = 0; i < 4; ++i) {
;       int c = tl + 256 * i;
;       int d = c >> 3, cc = c & 7;
;       rv[i] = *(const uint4*)(Vt + (size_t)d * ldv + key0 + cc * 8);
;     }
;     raux = (tid < 64) ? ctx.aux(key0 + tid) : 0.f;
;   };
;   auto sstore = [&]() {
;     stk(0, rk0); stk(1, rk1); stk(2, rk2); stk(3, rk3);
;     if (NKC > 4) { stk(4, rk4); stk(5, rk5); }
; #pragma unroll
;     for (int i = 0; i < 4; ++i) {
;       int c = tid + 256 * i;
;       int d = c >> 3, cc = c & 7;
;       uint2* dst = (uint2*)(Vs + d * 68 + cc * 8);
;       dst[0] = make_uint2(rv[i].x, rv[i].y);
;       dst[1] = make_uint2(rv[i].z, rv[i].w);
;     }
;     if (tid < 64) ((float*)(smem + AT_AUX))[tid] = raux;
;   };
;   if (PF) gload(tcur * 64);
;   while (tcur >= 0) {
;     __syncthreads();
;     if (!PF) gload(tcur * 64);
;     sstore();
;     __syncthreads();
;     int tnext = ctx.next(tcur);
;     if (PF && tnext >= 0) gload(tnext * 64);
.LBB0_332:
	s_or_b64 exec, exec, s[24:25]
	v_lshrrev_b32_e32 v0, 28, v169
	v_add_u32_e32 v0, v168, v0
	v_lshrrev_b32_e32 v2, 4, v0
	v_and_b32_e32 v0, 0xffffff0, v0
	v_sub_u32_e32 v0, v168, v0
	v_mul_lo_u32 v24, v2, s73
	v_add_u32_e32 v2, 0x100, v168
	v_lshlrev_b32_e32 v25, 4, v0
	v_ashrrev_i32_e32 v0, 31, v2
	v_lshrrev_b32_e32 v0, 28, v0
	v_add_u32_e32 v0, v2, v0
	v_lshrrev_b32_e32 v3, 4, v0
	v_and_b32_e32 v0, 0xffffff0, v0
	v_sub_u32_e32 v0, v2, v0
	v_mul_lo_u32 v26, v3, s73
	v_add_u32_e32 v3, 0x200, v168
	v_lshlrev_b32_e32 v27, 4, v0
	v_ashrrev_i32_e32 v0, 31, v3
	v_lshrrev_b32_e32 v0, 28, v0
	v_add_u32_e32 v0, v3, v0
	v_lshrrev_b32_e32 v4, 4, v0
	v_and_b32_e32 v0, 0xffffff0, v0
	v_sub_u32_e32 v0, v3, v0
	v_mul_lo_u32 v28, v4, s73
	v_add_u32_e32 v4, 0x300, v168
	v_lshlrev_b32_e32 v29, 4, v0
	v_ashrrev_i32_e32 v0, 31, v4
	v_lshrrev_b32_e32 v0, 28, v0
	v_add_u32_e32 v0, v4, v0
	v_lshrrev_b32_e32 v5, 4, v0
	v_and_b32_e32 v0, 0xffffff0, v0
	v_sub_u32_e32 v0, v4, v0
	v_lshlrev_b32_e32 v31, 4, v0
	v_lshlrev_b32_e32 v0, 4, v168
	v_and_b32_e32 v0, 0x70, v0
	v_lshrrev_b32_e32 v2, 3, v2
	v_mad_u64_u32 v[18:19], s[24:25], v2, s68, v[0:1]
	v_lshrrev_b32_e32 v2, 3, v3
	v_mad_u64_u32 v[20:21], s[24:25], v2, s68, v[0:1]
	v_lshrrev_b32_e32 v2, 3, v4
	v_mul_lo_u32 v30, v5, s73
	v_lshrrev_b32_e32 v5, 3, v168
	v_mad_u64_u32 v[22:23], s[24:25], v2, s68, v[0:1]
	v_mov_b32_e32 v14, v1
	v_mov_b32_e32 v15, v1
	v_mad_u64_u32 v[16:17], s[24:25], v5, s68, v[0:1]
	v_mov_b32_e32 v0, v1
	v_mov_b32_e32 v2, v1
	v_mov_b32_e32 v3, v1
	v_mov_b32_e32 v4, v1
	v_mov_b32_e32 v5, v1
	v_mov_b32_e32 v6, v1
	v_mov_b32_e32 v7, v1
	v_mov_b32_e32 v8, v1
	v_mov_b32_e32 v9, v1
	v_mov_b32_e32 v10, v1
	v_mov_b32_e32 v11, v1
	v_mov_b32_e32 v12, v1
	v_mov_b32_e32 v13, v1
	v_add_u32_e32 v176, v24, v25
	v_add_u32_e32 v177, v26, v27
	v_add_u32_e32 v178, v28, v29
	v_add_u32_e32 v179, v30, v31
	v_add_u32_e32 v182, 0x6400, v18
	v_add_u32_e32 v183, 0x6400, v20
	v_add_u32_e32 v184, 0x6400, v22
	v_mov_b64_e32 v[64:65], v[14:15]
	v_mov_b64_e32 v[48:49], v[14:15]
	v_mov_b64_e32 v[32:33], v[14:15]
	v_add_u32_e32 v181, 0x6400, v16
	v_mov_b64_e32 v[62:63], v[12:13]
	v_mov_b64_e32 v[60:61], v[10:11]
	v_mov_b64_e32 v[58:59], v[8:9]
	v_mov_b64_e32 v[56:57], v[6:7]
	v_mov_b64_e32 v[54:55], v[4:5]
	v_mov_b64_e32 v[52:53], v[2:3]
	v_mov_b64_e32 v[50:51], v[0:1]
	v_mov_b64_e32 v[46:47], v[12:13]
	v_mov_b64_e32 v[44:45], v[10:11]
	v_mov_b64_e32 v[42:43], v[8:9]
	v_mov_b64_e32 v[40:41], v[6:7]
	v_mov_b64_e32 v[38:39], v[4:5]
	v_mov_b64_e32 v[36:37], v[2:3]
	v_mov_b64_e32 v[34:35], v[0:1]
	v_mov_b64_e32 v[30:31], v[12:13]
	v_mov_b64_e32 v[28:29], v[10:11]
	v_mov_b64_e32 v[26:27], v[8:9]
	v_mov_b64_e32 v[24:25], v[6:7]
	v_mov_b64_e32 v[22:23], v[4:5]
	v_mov_b64_e32 v[20:21], v[2:3]
	v_mov_b64_e32 v[18:19], v[0:1]
	v_mov_b64_e32 v[16:17], v[14:15]
	s_lshl_b32 s1, s26, 1
	v_lshlrev_b32_e32 v169, 2, v168
	v_or_b32_e32 v175, 31, v174
	s_mov_b32 s26, 0
	v_mov_b32_e32 v193, 0xf149f2ca
	s_mov_b32 s51, 63
	v_mov_b64_e32 v[14:15], v[12:13]
	v_mov_b64_e32 v[12:13], v[10:11]
	v_mov_b64_e32 v[10:11], v[8:9]
	v_mov_b64_e32 v[8:9], v[6:7]
	v_mov_b64_e32 v[6:7], v[4:5]
	v_mov_b64_e32 v[4:5], v[2:3]
	v_mov_b64_e32 v[2:3], v[0:1]
	v_lshrrev_b32_e32 v248, 4, v189
	v_mul_u32_u24_e32 v248, 0x3900, v248
	v_and_b32_e32 v249, 15, v189
	v_lshl_add_u32 v248, v249, 4, v248
	v_lshrrev_b32_e32 v249, 3, v189
	v_lshlrev_b32_e32 v249, 14, v249
	v_and_b32_e32 v250, 7, v189
	v_lshl_or_b32 v249, v250, 4, v249
.LBB0_333:
	s_barrier
	s_waitcnt vmcnt(6)
	ds_write_b128 v176, v[130:133]
	ds_write_b128 v177, v[134:137]
	s_waitcnt vmcnt(5)
	ds_write_b128 v178, v[138:141]
	s_waitcnt vmcnt(4)
	ds_write_b128 v179, v[142:145]
	s_waitcnt vmcnt(3)
	ds_write2_b64 v181, v[146:147], v[148:149] offset1:1
	s_waitcnt vmcnt(2)
	ds_write2_b64 v182, v[150:151], v[152:153] offset1:1
	s_waitcnt vmcnt(1)
	ds_write2_b64 v183, v[154:155], v[156:157] offset1:1
	s_waitcnt vmcnt(0)
	ds_write2_b64 v184, v[158:159], v[160:161] offset1:1
	s_lshl_b32 s52, s26, 1
	s_andn2_b32 s52, s52, 3
	v_mov_b32_e32 v0, s52
	s_and_saveexec_b64 s[24:25], s[8:9]
	ds_read_b32 v0, v0 offset:43264
	s_waitcnt lgkmcnt(0)
	v_add_f32_e32 v0, v180, v0
	v_mul_f32_e32 v0, 0x3fb8aa3b, v0
	ds_write_b32 v169, v0 offset:43008
	s_or_b64 exec, exec, s[24:25]
	s_add_i32 s52, s26, 1
	s_cmp_le_u32 s26, s1
	s_cselect_b32 s26, s52, -1
	s_cmp_lt_i32 s26, 0
	s_cselect_b64 s[24:25], -1, 0
	s_and_b64 vcc, exec, s[24:25]
	s_waitcnt lgkmcnt(0)
	s_barrier
	s_cbranch_vccnz .LBB0_339
	s_lshl_b32 s64, s26, 6
	v_mov_b32_e32 v180, 0
	s_mul_i32 s26, s64, s70
	s_add_u32 s34, s12, s26
	s_addc_u32 s35, s13, 0
	global_load_dwordx4 v[130:133], v248, s[34:35]
	s_add_u32 s34, s34, 0x39000
	s_addc_u32 s35, s35, 0
	global_load_dwordx4 v[134:137], v248, s[34:35]
	s_add_u32 s34, s34, 0x39000
	s_addc_u32 s35, s35, 0
	global_load_dwordx4 v[138:141], v248, s[34:35]
	s_add_u32 s34, s34, 0x39000
	s_addc_u32 s35, s35, 0
	global_load_dwordx4 v[142:145], v248, s[34:35]
	s_lshl_b32 s26, s64, 1
	s_add_u32 s34, s22, s26
	s_addc_u32 s35, s23, 0
	global_load_dwordx4 v[146:149], v249, s[34:35]
	s_add_u32 s34, s34, 0x80000
	s_addc_u32 s35, s35, 0
	global_load_dwordx4 v[150:153], v249, s[34:35]
	s_add_u32 s34, s34, 0x80000
	s_addc_u32 s35, s35, 0
	global_load_dwordx4 v[154:157], v249, s[34:35]
	s_add_u32 s34, s34, 0x80000
	s_addc_u32 s35, s35, 0
	global_load_dwordx4 v[158:161], v249, s[34:35]
	s_lshl_b32 s26, s64, 2
	s_add_u32 s34, s20, s26
	s_addc_u32 s35, s21, 0
	s_and_saveexec_b64 s[26:27], s[8:9]
	global_load_dword v180, v169, s[34:35]

; __global__ void __launch_bounds__(256, LB2) mega(Params p, int ph_lo, int ph_hi) {
;     ...
;       for (int qd_ = 0; qd_ < 8; ++qd_) {
;       const int xq_ = ((bid & 7) + qd_) & 7;
;       for (;;) {
;         const int i_ = fetch_task(CTR + 64 + ph * 8 + xq_);
;         if (i_ >= 128) break;
;         const int tt_ = 2 * ((i_ >> 1) * 8 + xq_) + (i_ & 1);
;         const int t = tt_ >> 1;
.LBB0_462:
	v_mov_b32_e32 v213, 0x12400
	v_mov_b32_e32 v214, 0x12404
	v_mov_b32_e32 v215, 0x461c4000
	v_mov_b32_e32 v216, 0x37000000
	v_mov_b32_e32 v217, 0x3c0881c4
	v_mov_b32_e32 v218, 0xbab64f3b
	v_mov_b32_e32 v224, 0x7f800000
	v_mov_b32_e32 v225, 0xffffffc0
	v_mov_b32_e32 v226, 0xffffffe0
	v_mov_b32_e32 v227, 0x7fc00000
	v_mov_b32_e32 v229, 0x3ecc95a3
	v_mov_b32_e32 v231, 0x12000
	v_mov_b32_e32 v232, 0x3fe
	v_mov_b32_e32 v188, 0x358637bd
	v_mov_b32_e32 v190, 0x3f317218
	s_and_b64 vcc, exec, s[0:1]
	s_cbranch_vccnz .LBB0_458

; DI int otid() { int z; asm volatile("s_mov_b32 %0, 0" : "=s"(z)); return (int)threadIdx.x + z; }
;   DI float aux(int key) const { return (cuml[key] + cpre[key >> 7]) * LOG2E; }
;           DI float aux(int key) const { int n = key < 511 ? key : 510; return __int_as_float(pos[16 * n + 31]); }
;   DI float aux(int key) const { return __int_as_float(pos[key]); }
;   DI float aux(int key) const { return __int_as_float(pos[key]); }
; template <int DK, bool PV, bool PF, class Ctx>
; DI void attn_run(const bf16x8 (&qf)[DK / 16], f32x16 (&o)[4], float& m, float& l, const bf16* K1, int ldk1,
;                  const bf16* K2, int ldk2, const bf16* Vt, int ldv, int first, Ctx& ctx, char* smem) {
;     ...
;   auto ldk = [&](int i, int key0) -> uint4 {
;     int c = otid() + 256 * i;
;     int row = c / CPR, cc = c % CPR;
;     const bf16* src;
;     if (DK == 128 || cc < 16) src = K1 + (size_t)(key0 + row) * ldk1 + cc * 8;
;     else src = K2 + (size_t)(key0 + row) * ldk2 + (cc - 16) * 8;
;     return *(const uint4*)src;
;   };
;   auto stk = [&](int i, const uint4& v) {
;     int c = tid + 256 * i;
;     int row = c / CPR, cc = c % CPR;
;     *(uint4*)(Ks + row * (DK + 8) + cc * 8) = v;
;   };
;   auto gload = [&](int key0) {
;     rk0 = ldk(0, key0); rk1 = ldk(1, key0); rk2 = ldk(2, key0); rk3 = ldk(3, key0);
;     if (NKC > 4) { rk4 = ldk(4, key0); rk5 = ldk(5, key0); }
;     const int tl = otid();
; #pragma unroll
;     for (int i = 0; i < 4; ++i) {
;       int c = tl + 256 * i;
;       int d = c >> 3, cc = c & 7;
;       rv[i] = *(const uint4*)(Vt + (size_t)d * ldv + key0 + cc * 8);
;     }
;     raux = (tid < 64) ? ctx.aux(key0 + tid) : 0.f;
; __global__ void __launch_bounds__(256, LB2) mega(Params p, int ph_lo, int ph_hi) {
;     ...
;           const int qt = 63 - (t >> 3), head = t & 7;
;           const int q0w = qt * 128 + w * 32, tq = q0w + r;
;           bf16x8 qf[12];
;           load_q<192>(qf, (const bf16*)(ws + WS_QMLA) + (size_t)tq * 1536 + head * 192, h);
;           f32x16 o[4];
;           zero_o(o);
;           float m = NEG, l = 0.f;
;           CtxCausal ctx{tq, q0w, 2 * qt + 1, 0.07216878364870322f * LOG2E};
;           attn_run<192, true, true>(qf, o, m, l, (const bf16*)(ws + WS_KMLA) + head * 128, 1024, P + 6656, NPO,
;                               (const bf16*)(ws + WS_VTMLA) + (size_t)head * 128 * L, L, 0, ctx, smem);
.LBB0_850:
	s_and_b64 vcc, exec, s[0:1]
	s_cbranch_vccz .LBB0_461
	s_ashr_i32 s0, s51, 1
	s_sub_i32 s10, 63, s0
	s_lshl_b32 s0, s10, 7
	v_lshl_add_u32 v186, v155, 5, s0
	v_or_b32_e32 v193, v186, v157
	v_mov_b64_e32 v[2:3], s[48:49]
	s_movk_i32 s0, 0xc00
	v_mad_i64_i32 v[2:3], s[0:1], v193, s0, v[2:3]
	s_mov_b32 s51, s65
	v_lshl_add_u64 v[2:3], v[2:3], 0, s[50:51]
	v_lshlrev_b32_e32 v0, 4, v191
	v_lshl_add_u64 v[2:3], v[2:3], 0, v[0:1]
	s_mov_b64 s[0:1], 0xfed7000
	v_lshl_add_u64 v[4:5], v[2:3], 0, s[0:1]
	v_add_co_u32_e32 v2, vcc, 0xfed7000, v2
	s_add_u32 s0, s48, s97
	s_nop 0
	v_addc_co_u32_e32 v3, vcc, 0, v3, vcc
	global_load_dwordx4 v[98:101], v[4:5], off offset:32
	global_load_dwordx4 v[102:105], v[4:5], off offset:64
	global_load_dwordx4 v[106:109], v[4:5], off offset:96
	global_load_dwordx4 v[110:113], v[4:5], off offset:128
	global_load_dwordx4 v[114:117], v[4:5], off offset:160
	global_load_dwordx4 v[118:121], v[4:5], off offset:192
	global_load_dwordx4 v[122:125], v[4:5], off offset:224
	global_load_dwordx4 v[126:129], v[4:5], off offset:256
	global_load_dwordx4 v[130:133], v[4:5], off offset:288
	global_load_dwordx4 v[134:137], v[4:5], off offset:320
	global_load_dwordx4 v[138:141], v[2:3], off
	global_load_dwordx4 v[142:145], v[4:5], off offset:352
	s_mov_b32 s11, 0
	s_mov_b32 s6, 0
	s_addc_u32 s1, s49, 0
	v_add_u32_e32 v0, s6, v189
	v_mul_hi_i32 v2, v0, s58
	v_lshrrev_b32_e32 v3, 31, v2
	v_ashrrev_i32_e32 v2, 2, v2
	v_add_u32_e32 v4, v2, v3
	v_mul_lo_u32 v2, v4, 24
	s_add_u32 s0, s0, 0x116d7000
	v_sub_u32_e32 v0, v0, v2
	s_addc_u32 s1, s1, 0
	v_cmp_lt_i32_e32 vcc, 15, v0
	v_ashrrev_i32_e32 v5, 31, v4
	v_lshlrev_b32_e32 v2, 3, v0
	s_and_saveexec_b64 s[6:7], vcc
	s_xor_b64 s[6:7], exec, s[6:7]
	v_mov_b64_e32 v[6:7], s[94:95]
	v_mad_i64_i32 v[4:5], s[12:13], v4, s67, v[6:7]
	v_mov_b32_e32 v3, v1
	v_lshl_add_u64 v[2:3], v[2:3], 1, v[4:5]
	v_lshl_add_u64 v[6:7], v[2:3], 0, s[80:81]
	s_andn2_saveexec_b64 s[6:7], s[6:7]
	v_lshlrev_b64 v[4:5], 11, v[4:5]
	v_lshl_add_u64 v[4:5], s[0:1], 0, v[4:5]
	v_ashrrev_i32_e32 v3, 31, v2
	v_lshl_add_u64 v[6:7], v[2:3], 1, v[4:5]
	s_or_b64 exec, exec, s[6:7]
	global_load_dwordx4 v[146:149], v[6:7], off
	s_mov_b32 s6, 0
	s_nop 0
	v_add_u32_e32 v0, s6, v208
	v_mul_hi_i32 v2, v0, s58
	v_lshrrev_b32_e32 v3, 31, v2
	v_ashrrev_i32_e32 v2, 2, v2
	v_add_u32_e32 v4, v2, v3
	v_mul_lo_u32 v2, v4, 24
	v_sub_u32_e32 v0, v0, v2
	v_cmp_lt_i32_e32 vcc, 15, v0
	v_ashrrev_i32_e32 v5, 31, v4
	v_lshlrev_b32_e32 v2, 3, v0
	s_and_saveexec_b64 s[6:7], vcc
	s_xor_b64 s[6:7], exec, s[6:7]
	v_mov_b64_e32 v[6:7], s[94:95]
	v_mad_i64_i32 v[4:5], s[12:13], v4, s67, v[6:7]
	v_mov_b32_e32 v3, v1
	v_lshl_add_u64 v[2:3], v[2:3], 1, v[4:5]
	v_lshl_add_u64 v[6:7], v[2:3], 0, s[80:81]
	s_andn2_saveexec_b64 s[6:7], s[6:7]
	v_lshlrev_b64 v[4:5], 11, v[4:5]
	v_lshl_add_u64 v[4:5], s[0:1], 0, v[4:5]
	v_ashrrev_i32_e32 v3, 31, v2
	v_lshl_add_u64 v[6:7], v[2:3], 1, v[4:5]
	s_or_b64 exec, exec, s[6:7]
	global_load_dwordx4 v[150:153], v[6:7], off
	s_mov_b32 s6, 0
	s_nop 0
	v_add_u32_e32 v0, s6, v209
	v_mul_hi_i32 v2, v0, s58
	v_lshrrev_b32_e32 v3, 31, v2
	v_ashrrev_i32_e32 v2, 2, v2
	v_add_u32_e32 v4, v2, v3
	v_mul_lo_u32 v2, v4, 24
	v_sub_u32_e32 v0, v0, v2
	v_cmp_lt_i32_e32 vcc, 15, v0
	v_ashrrev_i32_e32 v5, 31, v4
	v_lshlrev_b32_e32 v2, 3, v0
	s_and_saveexec_b64 s[6:7], vcc
	s_xor_b64 s[6:7], exec, s[6:7]
	v_mov_b64_e32 v[6:7], s[94:95]
	v_mad_i64_i32 v[4:5], s[12:13], v4, s67, v[6:7]
	v_mov_b32_e32 v3, v1
	v_lshl_add_u64 v[2:3], v[2:3], 1, v[4:5]
	v_lshl_add_u64 v[6:7], v[2:3], 0, s[80:81]
	s_andn2_saveexec_b64 s[6:7], s[6:7]
	v_lshlrev_b64 v[4:5], 11, v[4:5]
	v_lshl_add_u64 v[4:5], s[0:1], 0, v[4:5]
	v_ashrrev_i32_e32 v3, 31, v2
	v_lshl_add_u64 v[6:7], v[2:3], 1, v[4:5]
	s_or_b64 exec, exec, s[6:7]
	global_load_dwordx4 v[154:157], v[6:7], off
	s_mov_b32 s6, 0
	s_nop 0
	v_add_u32_e32 v0, s6, v210
	v_mul_hi_i32 v2, v0, s58
	v_lshrrev_b32_e32 v3, 31, v2
	v_ashrrev_i32_e32 v2, 2, v2
	v_add_u32_e32 v4, v2, v3
	v_mul_lo_u32 v2, v4, 24
	v_sub_u32_e32 v0, v0, v2
	v_cmp_lt_i32_e32 vcc, 15, v0
	v_ashrrev_i32_e32 v5, 31, v4
	v_lshlrev_b32_e32 v2, 3, v0
	s_and_saveexec_b64 s[6:7], vcc
	s_xor_b64 s[6:7], exec, s[6:7]
	v_mov_b64_e32 v[6:7], s[94:95]
	v_mad_i64_i32 v[4:5], s[12:13], v4, s67, v[6:7]
	v_mov_b32_e32 v3, v1
	v_lshl_add_u64 v[2:3], v[2:3], 1, v[4:5]
	v_lshl_add_u64 v[6:7], v[2:3], 0, s[80:81]
	s_andn2_saveexec_b64 s[6:7], s[6:7]
	v_lshlrev_b64 v[4:5], 11, v[4:5]
	v_lshl_add_u64 v[4:5], s[0:1], 0, v[4:5]
	v_ashrrev_i32_e32 v3, 31, v2
	v_lshl_add_u64 v[6:7], v[2:3], 1, v[4:5]
	s_or_b64 exec, exec, s[6:7]
	global_load_dwordx4 v[158:161], v[6:7], off
	s_mov_b32 s6, 0
	s_nop 0
	v_add_u32_e32 v0, s6, v211
	v_mul_hi_i32 v2, v0, s58
	v_lshrrev_b32_e32 v3, 31, v2
	v_ashrrev_i32_e32 v2, 2, v2
	v_add_u32_e32 v4, v2, v3
	v_mul_lo_u32 v2, v4, 24
	v_sub_u32_e32 v0, v0, v2
	v_cmp_lt_i32_e32 vcc, 15, v0
	v_ashrrev_i32_e32 v5, 31, v4
	v_lshlrev_b32_e32 v2, 3, v0
	s_and_saveexec_b64 s[6:7], vcc
	s_xor_b64 s[6:7], exec, s[6:7]
	v_mov_b64_e32 v[6:7], s[94:95]
	v_mad_i64_i32 v[4:5], s[12:13], v4, s67, v[6:7]
	v_mov_b32_e32 v3, v1
	v_lshl_add_u64 v[2:3], v[2:3], 1, v[4:5]
	v_lshl_add_u64 v[6:7], v[2:3], 0, s[80:81]
	s_andn2_saveexec_b64 s[6:7], s[6:7]
	v_lshlrev_b64 v[4:5], 11, v[4:5]
	v_lshl_add_u64 v[4:5], s[0:1], 0, v[4:5]
	v_ashrrev_i32_e32 v3, 31, v2
	v_lshl_add_u64 v[6:7], v[2:3], 1, v[4:5]
	s_or_b64 exec, exec, s[6:7]
	global_load_dwordx4 v[162:165], v[6:7], off
	s_mov_b32 s6, 0
	s_nop 0
	v_add_u32_e32 v0, s6, v212
	v_mul_hi_i32 v2, v0, s58
	v_lshrrev_b32_e32 v3, 31, v2
	v_ashrrev_i32_e32 v2, 2, v2
	v_add_u32_e32 v6, v2, v3
	v_mul_lo_u32 v2, v6, 24
; DI int otid() { int z; asm volatile("s_mov_b32 %0, 0" : "=s"(z)); return (int)threadIdx.x + z; }
;   DI float aux(int key) const { return (cuml[key] + cpre[key >> 7]) * LOG2E; }
;           DI float aux(int key) const { int n = key < 511 ? key : 510; return __int_as_float(pos[16 * n + 31]); }
;   DI float aux(int key) const { return __int_as_float(pos[key]); }
;   DI float aux(int key) const { return __int_as_float(pos[key]); }
; template <int DK, bool PV, bool PF, class Ctx>
; DI void attn_run(const bf16x8 (&qf)[DK / 16], f32x16 (&o)[4], float& m, float& l, const bf16* K1, int ldk1,
;                  const bf16* K2, int ldk2, const bf16* Vt, int ldv, int first, Ctx& ctx, char* smem) {
;     ...
;   auto gload = [&](int key0) {
;     rk0 = ldk(0, key0); rk1 = ldk(1, key0); rk2 = ldk(2, key0); rk3 = ldk(3, key0);
;     if (NKC > 4) { rk4 = ldk(4, key0); rk5 = ldk(5, key0); }
;     const int tl = otid();
; #pragma unroll
;     for (int i = 0; i < 4; ++i) {
;       int c = tl + 256 * i;
;       int d = c >> 3, cc = c & 7;
;       rv[i] = *(const uint4*)(Vt + (size_t)d * ldv + key0 + cc * 8);
;     }
;     raux = (tid < 64) ? ctx.aux(key0 + tid) : 0.f;
;   };
;   auto sstore = [&]() {
;     stk(0, rk0); stk(1, rk1); stk(2, rk2); stk(3, rk3);
;     if (NKC > 4) { stk(4, rk4); stk(5, rk5); }
; #pragma unroll
;     for (int i = 0; i < 4; ++i) {
;       int c = tid + 256 * i;
;       int d = c >> 3, cc = c & 7;
;       uint2* dst = (uint2*)(Vs + d * 68 + cc * 8);
;       dst[0] = make_uint2(rv[i].x, rv[i].y);
;       dst[1] = make_uint2(rv[i].z, rv[i].w);
;     }
;     if (tid < 64) ((float*)(smem + AT_AUX))[tid] = raux;
;   };
	v_sub_u32_e32 v0, v0, v2
	v_cmp_lt_i32_e32 vcc, 15, v0
	v_ashrrev_i32_e32 v7, 31, v6
	v_lshlrev_b32_e32 v4, 3, v0
	s_and_saveexec_b64 s[6:7], vcc
	s_xor_b64 s[6:7], exec, s[6:7]
	v_mov_b64_e32 v[2:3], s[94:95]
	v_mad_i64_i32 v[2:3], s[12:13], v6, s67, v[2:3]
	v_mov_b32_e32 v5, v1
	v_lshl_add_u64 v[2:3], v[4:5], 1, v[2:3]
	v_lshl_add_u64 v[2:3], v[2:3], 0, s[80:81]
	s_andn2_saveexec_b64 s[6:7], s[6:7]
	v_lshlrev_b64 v[2:3], 11, v[6:7]
	v_lshl_add_u64 v[2:3], s[0:1], 0, v[2:3]
	v_ashrrev_i32_e32 v5, 31, v4
	v_lshl_add_u64 v[2:3], v[4:5], 1, v[2:3]
	s_or_b64 exec, exec, s[6:7]
	s_lshl_b32 s34, s10, 1
	s_add_u32 s6, s48, s19
	global_load_dwordx4 v[166:169], v[2:3], off
	s_mov_b32 s10, 0
	s_addc_u32 s7, s49, 0
	v_add_u32_e32 v7, s10, v189
	v_ashrrev_i32_e32 v2, 3, v7
	v_add_u32_e32 v4, 0x100, v7
	s_add_u32 s6, s6, 0x126d7000
	v_ashrrev_i32_e32 v3, 31, v2
	v_ashrrev_i32_e32 v4, 3, v4
	s_addc_u32 s7, s7, 0
	v_lshlrev_b64 v[2:3], 14, v[2:3]
	v_lshlrev_b32_e32 v0, 4, v7
	v_ashrrev_i32_e32 v5, 31, v4
	v_lshl_add_u64 v[2:3], s[6:7], 0, v[2:3]
	v_and_b32_e32 v0, 0x70, v0
	v_lshlrev_b64 v[4:5], 14, v[4:5]
	v_lshl_add_u64 v[2:3], v[2:3], 0, v[0:1]
	v_lshl_add_u64 v[4:5], s[6:7], 0, v[4:5]
	v_lshl_add_u64 v[4:5], v[4:5], 0, v[0:1]
	global_load_dwordx4 v[170:173], v[2:3], off
	global_load_dwordx4 v[174:177], v[4:5], off
	v_add_u32_e32 v2, 0x200, v7
	v_ashrrev_i32_e32 v2, 3, v2
	v_add_u32_e32 v4, 0x300, v7
	v_ashrrev_i32_e32 v3, 31, v2
	v_ashrrev_i32_e32 v4, 3, v4
	v_lshlrev_b64 v[2:3], 14, v[2:3]
	v_ashrrev_i32_e32 v5, 31, v4
	v_lshl_add_u64 v[2:3], s[6:7], 0, v[2:3]
	v_lshlrev_b64 v[4:5], 14, v[4:5]
	v_lshl_add_u64 v[2:3], v[2:3], 0, v[0:1]
	v_lshl_add_u64 v[4:5], s[6:7], 0, v[4:5]
	v_lshl_add_u64 v[4:5], v[4:5], 0, v[0:1]
	global_load_dwordx4 v[178:181], v[2:3], off
	global_load_dwordx4 v[182:185], v[4:5], off
	v_add_u32_e32 v6, s11, v189
	v_mul_hi_i32 v0, v6, s58
	v_lshrrev_b32_e32 v2, 31, v0
	v_ashrrev_i32_e32 v0, 2, v0
	v_add_u32_e32 v0, v0, v2
	v_mul_lo_u32 v2, v0, 24
	v_sub_u32_e32 v2, v6, v2
	v_lshlrev_b32_e32 v25, 4, v2
	v_add_u32_e32 v2, 0x100, v6
	v_mul_lo_u32 v24, v0, s33
	v_mul_hi_i32 v0, v2, s58
	v_lshrrev_b32_e32 v3, 31, v0
	v_ashrrev_i32_e32 v0, 2, v0
	v_add_u32_e32 v0, v0, v3
	v_mul_lo_u32 v3, v0, 24
	v_sub_u32_e32 v3, v2, v3
	v_lshlrev_b32_e32 v27, 4, v3
	v_add_u32_e32 v3, 0x200, v6
	v_mul_lo_u32 v26, v0, s33
	v_mul_hi_i32 v0, v3, s58
	v_lshrrev_b32_e32 v4, 31, v0
	v_ashrrev_i32_e32 v0, 2, v0
	v_add_u32_e32 v0, v0, v4
	v_mul_lo_u32 v4, v0, 24
	v_sub_u32_e32 v4, v3, v4
	v_lshlrev_b32_e32 v29, 4, v4
	v_add_u32_e32 v4, 0x300, v6
	v_mul_lo_u32 v28, v0, s33
	v_mul_hi_i32 v0, v4, s58
	v_lshrrev_b32_e32 v5, 31, v0
	v_ashrrev_i32_e32 v0, 2, v0
	v_add_u32_e32 v0, v0, v5
	v_mul_lo_u32 v5, v0, 24
	v_sub_u32_e32 v5, v4, v5
	v_mul_lo_u32 v30, v0, s33
	v_add_u32_e32 v0, 0x400, v6
	v_lshlrev_b32_e32 v31, 4, v5
	v_mul_hi_i32 v5, v0, s58
	v_lshrrev_b32_e32 v7, 31, v5
	v_ashrrev_i32_e32 v5, 2, v5
	v_add_u32_e32 v5, v5, v7
	v_mul_lo_u32 v7, v5, 24
	v_sub_u32_e32 v0, v0, v7
	v_lshlrev_b32_e32 v33, 4, v0
	v_add_u32_e32 v0, 0x500, v6
	v_mul_lo_u32 v32, v5, s33
	v_mul_hi_i32 v5, v0, s58
	v_lshrrev_b32_e32 v7, 31, v5
	v_ashrrev_i32_e32 v5, 2, v5
	v_add_u32_e32 v5, v5, v7
	v_mul_lo_u32 v7, v5, 24
	v_sub_u32_e32 v0, v0, v7
	v_lshlrev_b32_e32 v35, 4, v0
	v_lshlrev_b32_e32 v0, 4, v6
	v_and_b32_e32 v0, 0x70, v0
	v_lshrrev_b32_e32 v2, 3, v2
	v_mad_u64_u32 v[18:19], s[10:11], v2, s68, v[0:1]
	v_lshrrev_b32_e32 v2, 3, v3
	v_mul_lo_u32 v34, v5, s33
	v_lshrrev_b32_e32 v5, 3, v6
	v_mad_u64_u32 v[20:21], s[10:11], v2, s68, v[0:1]
	v_lshrrev_b32_e32 v2, 3, v4
	v_mad_u64_u32 v[16:17], s[10:11], v5, s68, v[0:1]
	v_mad_u64_u32 v[22:23], s[10:11], v2, s68, v[0:1]
	v_mov_b32_e32 v14, v1
	v_mov_b32_e32 v15, v1
	v_cmp_gt_i32_e64 s[10:11], 64, v6
	v_lshlrev_b32_e32 v195, 2, v6
	v_mov_b32_e32 v0, v1
	v_mov_b32_e32 v2, v1
	v_mov_b32_e32 v3, v1
	v_mov_b32_e32 v4, v1
	v_mov_b32_e32 v5, v1
	v_mov_b32_e32 v6, v1
	v_mov_b32_e32 v7, v1
	v_mov_b32_e32 v8, v1
	v_mov_b32_e32 v9, v1
	v_mov_b32_e32 v10, v1
	v_mov_b32_e32 v11, v1
	v_mov_b32_e32 v12, v1
	v_mov_b32_e32 v13, v1
	v_add_u32_e32 v197, v24, v25
	v_add_u32_e32 v198, v26, v27
	v_add_u32_e32 v199, v28, v29
	v_add_u32_e32 v200, v30, v31
	v_add_u32_e32 v201, v32, v33
	v_add_u32_e32 v202, v34, v35
	v_add_u32_e32 v204, 0x6400, v18
	v_add_u32_e32 v205, 0x6400, v20
	v_add_u32_e32 v206, 0x6400, v22
	v_mov_b64_e32 v[64:65], v[14:15]
	v_mov_b64_e32 v[48:49], v[14:15]
	v_mov_b64_e32 v[32:33], v[14:15]
	v_add_u32_e32 v203, 0x6400, v16
	v_mov_b64_e32 v[62:63], v[12:13]
	v_mov_b64_e32 v[60:61], v[10:11]
	v_mov_b64_e32 v[58:59], v[8:9]
	v_mov_b64_e32 v[56:57], v[6:7]
	v_mov_b64_e32 v[54:55], v[4:5]
	v_mov_b64_e32 v[52:53], v[2:3]
	v_mov_b64_e32 v[50:51], v[0:1]
	v_mov_b64_e32 v[46:47], v[12:13]
	v_mov_b64_e32 v[44:45], v[10:11]
	v_mov_b64_e32 v[42:43], v[8:9]
	v_mov_b64_e32 v[40:41], v[6:7]
	v_mov_b64_e32 v[38:39], v[4:5]
	v_mov_b64_e32 v[36:37], v[2:3]
	v_mov_b64_e32 v[34:35], v[0:1]
	v_mov_b64_e32 v[30:31], v[12:13]
	v_mov_b64_e32 v[28:29], v[10:11]
	v_mov_b64_e32 v[26:27], v[8:9]
	v_mov_b64_e32 v[24:25], v[6:7]
	v_mov_b64_e32 v[22:23], v[4:5]
; DI int otid() { int z; asm volatile("s_mov_b32 %0, 0" : "=s"(z)); return (int)threadIdx.x + z; }
;   DI float aux(int key) const { return (cuml[key] + cpre[key >> 7]) * LOG2E; }
;           DI float aux(int key) const { int n = key < 511 ? key : 510; return __int_as_float(pos[16 * n + 31]); }
;   DI int next(int t) const { for (int j = t + 1; j < 128; ++j) if (inu(j) && !farj(j)) return j; return -1; }
; template <int DK, bool PV, bool PF, class Ctx>
; DI void attn_run(const bf16x8 (&qf)[DK / 16], f32x16 (&o)[4], float& m, float& l, const bf16* K1, int ldk1,
;                  const bf16* K2, int ldk2, const bf16* Vt, int ldv, int first, Ctx& ctx, char* smem) {
;     ...
;   auto ldk = [&](int i, int key0) -> uint4 {
;     int c = otid() + 256 * i;
;     int row = c / CPR, cc = c % CPR;
;     const bf16* src;
;     if (DK == 128 || cc < 16) src = K1 + (size_t)(key0 + row) * ldk1 + cc * 8;
;     else src = K2 + (size_t)(key0 + row) * ldk2 + (cc - 16) * 8;
;     return *(const uint4*)src;
;   };
;   auto stk = [&](int i, const uint4& v) {
;     int c = tid + 256 * i;
;     int row = c / CPR, cc = c % CPR;
;     *(uint4*)(Ks + row * (DK + 8) + cc * 8) = v;
;   };
;   auto gload = [&](int key0) {
;     rk0 = ldk(0, key0); rk1 = ldk(1, key0); rk2 = ldk(2, key0); rk3 = ldk(3, key0);
;     if (NKC > 4) { rk4 = ldk(4, key0); rk5 = ldk(5, key0); }
;     const int tl = otid();
; #pragma unroll
;     for (int i = 0; i < 4; ++i) {
;       int c = tl + 256 * i;
;       int d = c >> 3, cc = c & 7;
;       rv[i] = *(const uint4*)(Vt + (size_t)d * ldv + key0 + cc * 8);
;     }
;     raux = (tid < 64) ? ctx.aux(key0 + tid) : 0.f;
;   };
;   auto sstore = [&]() {
;     stk(0, rk0); stk(1, rk1); stk(2, rk2); stk(3, rk3);
;     if (NKC > 4) { stk(4, rk4); stk(5, rk5); }
; #pragma unroll
;     for (int i = 0; i < 4; ++i) {
;       int c = tid + 256 * i;
;       int d = c >> 3, cc = c & 7;
;       uint2* dst = (uint2*)(Vs + d * 68 + cc * 8);
;       dst[0] = make_uint2(rv[i].x, rv[i].y);
;       dst[1] = make_uint2(rv[i].z, rv[i].w);
;     }
;     if (tid < 64) ((float*)(smem + AT_AUX))[tid] = raux;
;   };
;   if (PF) gload(tcur * 64);
;   while (tcur >= 0) {
;     __syncthreads();
;     if (!PF) gload(tcur * 64);
;     sstore();
;     __syncthreads();
;     int tnext = ctx.next(tcur);
;     if (PF && tnext >= 0) gload(tnext * 64);
	v_mov_b64_e32 v[20:21], v[2:3]
	v_mov_b64_e32 v[18:19], v[0:1]
	v_mov_b64_e32 v[16:17], v[14:15]
	v_or_b32_e32 v196, 31, v186
	s_mov_b32 s14, 0
	v_mov_b32_e32 v238, 0xf149f2ca
	v_mov_b32_e32 v194, 0
	s_mov_b32 s35, 63
	v_mov_b64_e32 v[14:15], v[12:13]
	v_mov_b64_e32 v[12:13], v[10:11]
	v_mov_b64_e32 v[10:11], v[8:9]
	v_mov_b64_e32 v[8:9], v[6:7]
	v_mov_b64_e32 v[6:7], v[4:5]
	v_mov_b64_e32 v[4:5], v[2:3]
	v_mov_b64_e32 v[2:3], v[0:1]
	s_mov_b32 s26, 0xaaaaaab
	s_sub_u32 s27, s0, s94
	v_mul_hi_u32 v253, v189, s26
	v_mul_u32_u24_e32 v188, 24, v253
	v_sub_u32_e32 v188, v189, v188
	v_lshlrev_b32_e32 v190, 4, v188
	v_mul_u32_u24_e32 v213, 0x3500, v253
	v_add3_u32 v213, v213, v190, s80
	v_lshl_add_u32 v253, v253, 11, v190
	v_add_u32_e32 v253, s27, v253
	v_cmp_lt_u32_e32 vcc, 15, v188
	v_mov_b32_e32 v224, 0x800
	v_mov_b32_e32 v190, 0x3500
	v_cndmask_b32_e32 v213, v253, v213, vcc
	v_cndmask_b32_e32 v224, v224, v190, vcc
	v_mul_hi_u32 v253, v208, s26
	v_mul_u32_u24_e32 v188, 24, v253
	v_sub_u32_e32 v188, v208, v188
	v_lshlrev_b32_e32 v190, 4, v188
	v_mul_u32_u24_e32 v214, 0x3500, v253
	v_add3_u32 v214, v214, v190, s80
	v_lshl_add_u32 v253, v253, 11, v190
	v_add_u32_e32 v253, s27, v253
	v_cmp_lt_u32_e32 vcc, 15, v188
	v_mov_b32_e32 v225, 0x800
	v_mov_b32_e32 v190, 0x3500
	v_cndmask_b32_e32 v214, v253, v214, vcc
	v_cndmask_b32_e32 v225, v225, v190, vcc
	v_mul_hi_u32 v253, v209, s26
	v_mul_u32_u24_e32 v188, 24, v253
	v_sub_u32_e32 v188, v209, v188
	v_lshlrev_b32_e32 v190, 4, v188
	v_mul_u32_u24_e32 v215, 0x3500, v253
	v_add3_u32 v215, v215, v190, s80
	v_lshl_add_u32 v253, v253, 11, v190
	v_add_u32_e32 v253, s27, v253
	v_cmp_lt_u32_e32 vcc, 15, v188
	v_mov_b32_e32 v226, 0x800
	v_mov_b32_e32 v190, 0x3500
	v_cndmask_b32_e32 v215, v253, v215, vcc
	v_cndmask_b32_e32 v226, v226, v190, vcc
	v_mul_hi_u32 v253, v210, s26
	v_mul_u32_u24_e32 v188, 24, v253
	v_sub_u32_e32 v188, v210, v188
	v_lshlrev_b32_e32 v190, 4, v188
	v_mul_u32_u24_e32 v216, 0x3500, v253
	v_add3_u32 v216, v216, v190, s80
	v_lshl_add_u32 v253, v253, 11, v190
	v_add_u32_e32 v253, s27, v253
	v_cmp_lt_u32_e32 vcc, 15, v188
	v_mov_b32_e32 v227, 0x800
	v_mov_b32_e32 v190, 0x3500
	v_cndmask_b32_e32 v216, v253, v216, vcc
	v_cndmask_b32_e32 v227, v227, v190, vcc
	v_mul_hi_u32 v253, v211, s26
	v_mul_u32_u24_e32 v188, 24, v253
	v_sub_u32_e32 v188, v211, v188
	v_lshlrev_b32_e32 v190, 4, v188
	v_mul_u32_u24_e32 v217, 0x3500, v253
	v_add3_u32 v217, v217, v190, s80
	v_lshl_add_u32 v253, v253, 11, v190
	v_add_u32_e32 v253, s27, v253
	v_cmp_lt_u32_e32 vcc, 15, v188
	v_mov_b32_e32 v229, 0x800
	v_mov_b32_e32 v190, 0x3500
	v_cndmask_b32_e32 v217, v253, v217, vcc
	v_cndmask_b32_e32 v229, v229, v190, vcc
	v_mul_hi_u32 v253, v212, s26
	v_mul_u32_u24_e32 v188, 24, v253
	v_sub_u32_e32 v188, v212, v188
	v_lshlrev_b32_e32 v190, 4, v188
	v_mul_u32_u24_e32 v218, 0x3500, v253
	v_add3_u32 v218, v218, v190, s80
	v_lshl_add_u32 v253, v253, 11, v190
	v_add_u32_e32 v253, s27, v253
	v_cmp_lt_u32_e32 vcc, 15, v188
	v_mov_b32_e32 v231, 0x800
	v_mov_b32_e32 v190, 0x3500
	v_cndmask_b32_e32 v218, v253, v218, vcc
	v_cndmask_b32_e32 v231, v231, v190, vcc
	v_lshrrev_b32_e32 v232, 3, v189
	v_lshlrev_b32_e32 v232, 14, v232
	v_and_b32_e32 v190, 7, v189
	v_lshl_or_b32 v232, v190, 4, v232
.LBB0_876:
	s_barrier
	s_waitcnt vmcnt(9)
	ds_write_b128 v197, v[146:149]
	s_waitcnt vmcnt(8)
	ds_write_b128 v198, v[150:153]
	s_waitcnt vmcnt(7)
	ds_write_b128 v199, v[154:157]
	s_waitcnt vmcnt(6)
	ds_write_b128 v200, v[158:161]
	s_waitcnt vmcnt(5)
	ds_write_b128 v201, v[162:165]
	s_waitcnt vmcnt(4)
	ds_write_b128 v202, v[166:169]
	s_waitcnt vmcnt(3)
	ds_write2_b64 v203, v[170:171], v[172:173] offset1:1
	s_waitcnt vmcnt(2)
	ds_write2_b64 v204, v[174:175], v[176:177] offset1:1
	s_waitcnt vmcnt(1)
	ds_write2_b64 v205, v[178:179], v[180:181] offset1:1
	s_waitcnt vmcnt(0)
	ds_write2_b64 v206, v[182:183], v[184:185] offset1:1
	s_and_saveexec_b64 s[12:13], s[10:11]
	ds_write_b32 v195, v1 offset:43008
	s_or_b64 exec, exec, s[12:13]
	s_add_i32 s36, s14, 1
	s_cmp_le_u32 s14, s34
	s_cselect_b32 s14, s36, -1
	s_cmp_lt_i32 s14, 0
	s_cselect_b64 s[12:13], -1, 0
	s_and_b64 vcc, exec, s[12:13]
	s_waitcnt lgkmcnt(0)
	s_barrier
	s_cbranch_vccnz .LBB0_904
	s_lshl_b32 s64, s14, 6
	v_mad_u32_u24 v66, s64, v224, v213
	v_mad_u32_u24 v67, s64, v225, v214
	v_mad_u32_u24 v68, s64, v226, v215
	v_mad_u32_u24 v69, s64, v227, v216
	v_mad_u32_u24 v70, s64, v229, v217
	v_mad_u32_u24 v71, s64, v231, v218
	global_load_dwordx4 v[146:149], v66, s[94:95]
	global_load_dwordx4 v[150:153], v67, s[94:95]
	global_load_dwordx4 v[154:157], v68, s[94:95]
	global_load_dwordx4 v[158:161], v69, s[94:95]
	global_load_dwordx4 v[162:165], v70, s[94:95]
	global_load_dwordx4 v[166:169], v71, s[94:95]
	s_lshl_b32 s14, s64, 1
	s_add_u32 s26, s6, s14
	s_addc_u32 s27, s7, 0
	global_load_dwordx4 v[170:173], v232, s[26:27]
	s_add_u32 s26, s26, 0x80000
	s_addc_u32 s27, s27, 0
	global_load_dwordx4 v[174:177], v232, s[26:27]
	s_add_u32 s26, s26, 0x80000
	s_addc_u32 s27, s27, 0
	global_load_dwordx4 v[178:181], v232, s[26:27]
	s_add_u32 s26, s26, 0x80000
	s_addc_u32 s27, s27, 0
	global_load_dwordx4 v[182:185], v232, s[26:27]
